# sample-tail offload: last 32 sample mixer items moved from WGs 0-3 second round to wave 0 of prompt WGs 176-207 (poll sub_barrier counter)
# speedup vs baseline: 1.0226x; 1.0110x over previous
.LBB0_228:
	s_movk_i32 s0, 0x1400
	s_movk_i32 s1, 0x1480
	s_barrier

.LBB0_232:
	v_readlane_b32 s0, v235, 45
	s_add_i32 s18, s18, s0
	v_readlane_b32 s0, v235, 46
	s_cmp_lt_i32 s18, s0
	s_cbranch_scc1 .LBB0_233
	s_cmpk_eq_i32 s0, 0x1400
	s_cbranch_scc0 ATH0_DONE
	s_sub_u32 s0, s2, 176
	s_cmp_lt_u32 s0, 32
	s_cbranch_scc0 .LBB0_307
	v_readlane_b32 s1, v235, 20
	s_cmp_eq_u32 s1, 0
	s_cbranch_scc0 .LBB0_307
	s_add_i32 s18, s0, 0x1480
	v_mov_b32_e32 v236, 0x3700
	s_movk_i32 s1, 0x2000
ATH0_POLL:
	global_load_dword v237, v236, s[78:79] sc1
	s_waitcnt vmcnt(0)
	v_readfirstlane_b32 s0, v237
	s_cmp_ge_u32 s0, 16
	s_cbranch_scc1 ATH0_GO
	s_sleep 4
	s_add_i32 s1, s1, -1
	s_cmp_eq_u32 s1, 0
	s_cbranch_scc0 ATH0_POLL
	s_branch .LBB0_307
ATH0_GO:
	buffer_inv sc1
	s_waitcnt vmcnt(0)
	s_movk_i32 s0, 0x14a0
	s_nop 0
	v_writelane_b32 v235, s0, 46
	s_branch .LBB0_233
ATH0_DONE:
	s_cmpk_eq_i32 s0, 0x14a0
	s_cbranch_scc0 .LBB0_307
	s_movk_i32 s0, 0x1400
	s_nop 0
	v_writelane_b32 v235, s0, 46
	s_branch .LBB0_307

.LBB0_940:
	s_add_i32 s26, s26, s80
	v_readlane_b32 s0, v235, 46
	s_cmp_lt_i32 s26, s0
	s_cbranch_scc1 .LBB0_941
	s_cmpk_eq_i32 s0, 0x1400
	s_cbranch_scc0 ATH1_DONE
	s_sub_u32 s0, s2, 176
	s_cmp_lt_u32 s0, 32
	s_cbranch_scc0 .LBB0_1015
	v_readlane_b32 s1, v235, 20
	s_cmp_eq_u32 s1, 0
	s_cbranch_scc0 .LBB0_1015
	s_add_i32 s26, s0, 0x1480
	v_mov_b32_e32 v236, 0x3800
	s_movk_i32 s1, 0x2000
ATH1_POLL:
	global_load_dword v237, v236, s[78:79] sc1
	s_waitcnt vmcnt(0)
	v_readfirstlane_b32 s0, v237
	s_cmp_ge_u32 s0, 16
	s_cbranch_scc1 ATH1_GO
	s_sleep 4
	s_add_i32 s1, s1, -1
	s_cmp_eq_u32 s1, 0
	s_cbranch_scc0 ATH1_POLL
	s_branch .LBB0_1015
ATH1_GO:
	buffer_inv sc1
	s_waitcnt vmcnt(0)
	s_movk_i32 s0, 0x14a0
	s_nop 0
	v_writelane_b32 v235, s0, 46
	s_branch .LBB0_941
ATH1_DONE:
	s_cmpk_eq_i32 s0, 0x14a0
	s_cbranch_scc0 .LBB0_1015
	s_movk_i32 s0, 0x1400
	s_nop 0
	v_writelane_b32 v235, s0, 46
	s_branch .LBB0_1015

.LBB0_1649:
	s_add_i32 s30, s30, s80
	v_readlane_b32 s0, v235, 46
	s_cmp_lt_i32 s30, s0
	s_cbranch_scc1 .LBB0_1650
	s_cmpk_eq_i32 s0, 0x1400
	s_cbranch_scc0 ATH2_DONE
	s_sub_u32 s0, s2, 176
	s_cmp_lt_u32 s0, 32
	s_cbranch_scc0 .LBB0_1724
	v_readlane_b32 s1, v235, 20
	s_cmp_eq_u32 s1, 0
	s_cbranch_scc0 .LBB0_1724
	s_add_i32 s30, s0, 0x1480
	v_mov_b32_e32 v236, 0x3900
	s_movk_i32 s1, 0x2000
ATH2_POLL:
	global_load_dword v237, v236, s[78:79] sc1
	s_waitcnt vmcnt(0)
	v_readfirstlane_b32 s0, v237
	s_cmp_ge_u32 s0, 16
	s_cbranch_scc1 ATH2_GO
	s_sleep 4
	s_add_i32 s1, s1, -1
	s_cmp_eq_u32 s1, 0
	s_cbranch_scc0 ATH2_POLL
	s_branch .LBB0_1724
ATH2_GO:
	buffer_inv sc1
	s_waitcnt vmcnt(0)
	s_movk_i32 s0, 0x14a0
	s_nop 0
	v_writelane_b32 v235, s0, 46
	s_branch .LBB0_1650
ATH2_DONE:
	s_cmpk_eq_i32 s0, 0x14a0
	s_cbranch_scc0 .LBB0_1724
	s_movk_i32 s0, 0x1400
	s_nop 0
	v_writelane_b32 v235, s0, 46
	s_branch .LBB0_1724

.LBB0_2358:
	s_add_i32 s30, s30, s80
	v_readlane_b32 s0, v235, 46
	s_cmp_lt_i32 s30, s0
	s_cbranch_scc1 .LBB0_2359
	s_cmpk_eq_i32 s0, 0x1400
	s_cbranch_scc0 ATH3_DONE
	s_sub_u32 s0, s2, 176
	s_cmp_lt_u32 s0, 32
	s_cbranch_scc0 .LBB0_2433
	v_readlane_b32 s1, v235, 20
	s_cmp_eq_u32 s1, 0
	s_cbranch_scc0 .LBB0_2433
	s_add_i32 s30, s0, 0x1480
	v_mov_b32_e32 v236, 0x3a00
	s_movk_i32 s1, 0x2000
ATH3_POLL:
	global_load_dword v237, v236, s[78:79] sc1
	s_waitcnt vmcnt(0)
	v_readfirstlane_b32 s0, v237
	s_cmp_ge_u32 s0, 16
	s_cbranch_scc1 ATH3_GO
	s_sleep 4
	s_add_i32 s1, s1, -1
	s_cmp_eq_u32 s1, 0
	s_cbranch_scc0 ATH3_POLL
	s_branch .LBB0_2433
ATH3_GO:
	buffer_inv sc1
	s_waitcnt vmcnt(0)
	s_movk_i32 s0, 0x14a0
	s_nop 0
	v_writelane_b32 v235, s0, 46
	s_branch .LBB0_2359
ATH3_DONE:
	s_cmpk_eq_i32 s0, 0x14a0
	s_cbranch_scc0 .LBB0_2433
	s_movk_i32 s0, 0x1400
	s_nop 0
	v_writelane_b32 v235, s0, 46
	s_branch .LBB0_2433
